# attention main loop: next K/V tile via LDS-DMA with inverse-swizzled source addresses (same LDS image), V transfer waited one half-step later with counted vmcnt; no staging VGPRs / ds_write_b128 in th
# speedup vs baseline: 1.0480x; 1.0072x over previous
.LBB0_387:
	v_max_f32_e32 v3, 0xf149f2ca, v3
	v_cndmask_b32_e64 v182, v3, v192, s[6:7]
	v_sub_f32_e32 v3, 0xf149f2ca, v3
	v_mul_f32_e32 v3, 0x3e0293ee, v3
	v_exp_f32_e32 v3, v3
	v_mul_f32_e32 v4, 0xbe0293ee, v182
	s_and_b32 s4, s33, 0x3fffffc0
	v_and_b32_e32 v206, 63, v49
	v_fmamk_f32 v5, v32, 0x3e0293ee, v4
	s_lshl_b32 s4, s4, 2
	v_fmamk_f32 v6, v33, 0x3e0293ee, v4
	v_fmamk_f32 v7, v34, 0x3e0293ee, v4
	v_fmamk_f32 v8, v35, 0x3e0293ee, v4
	v_fmamk_f32 v9, v36, 0x3e0293ee, v4
	v_fmamk_f32 v10, v37, 0x3e0293ee, v4
	v_fmamk_f32 v11, v38, 0x3e0293ee, v4
	v_fmamk_f32 v12, v39, 0x3e0293ee, v4
	v_fmamk_f32 v13, v40, 0x3e0293ee, v4
	v_fmamk_f32 v14, v41, 0x3e0293ee, v4
	v_fmamk_f32 v15, v42, 0x3e0293ee, v4
	v_fmamk_f32 v32, v43, 0x3e0293ee, v4
	v_fmamk_f32 v33, v44, 0x3e0293ee, v4
	v_fmamk_f32 v34, v45, 0x3e0293ee, v4
	v_fmamk_f32 v35, v46, 0x3e0293ee, v4
	v_fmamk_f32 v36, v47, 0x3e0293ee, v4
	v_pk_fma_f32 v[114:115], v[30:31], s[16:17], v[4:5] op_sel_hi:[1,0,0]
	v_pk_fma_f32 v[116:117], v[28:29], s[16:17], v[4:5] op_sel_hi:[1,0,0]
	v_pk_fma_f32 v[118:119], v[26:27], s[16:17], v[4:5] op_sel_hi:[1,0,0]
	v_pk_fma_f32 v[120:121], v[24:25], s[16:17], v[4:5] op_sel_hi:[1,0,0]
	v_pk_fma_f32 v[122:123], v[22:23], s[16:17], v[4:5] op_sel_hi:[1,0,0]
	v_pk_fma_f32 v[124:125], v[20:21], s[16:17], v[4:5] op_sel_hi:[1,0,0]
	v_pk_fma_f32 v[126:127], v[18:19], s[16:17], v[4:5] op_sel_hi:[1,0,0]
	v_pk_fma_f32 v[128:129], v[16:17], s[16:17], v[4:5] op_sel_hi:[1,0,0]
	s_add_i32 s4, s4, 0
	v_lshlrev_b32_e32 v4, 4, v206
	v_exp_f32_e32 v175, v5
	v_exp_f32_e32 v177, v6
	v_exp_f32_e32 v173, v7
	v_exp_f32_e32 v176, v8
	v_exp_f32_e32 v171, v9
	v_exp_f32_e32 v174, v10
	v_exp_f32_e32 v170, v11
	v_exp_f32_e32 v172, v12
	v_exp_f32_e32 v164, v13
	v_exp_f32_e32 v167, v14
	v_exp_f32_e32 v163, v15
	v_exp_f32_e32 v165, v32
	v_exp_f32_e32 v162, v33
	v_exp_f32_e32 v169, v34
	v_exp_f32_e32 v166, v35
	v_exp_f32_e32 v168, v36
	v_cndmask_b32_e64 v220, v3, 1.0, s[6:7]
	s_add_i32 s6, s4, 0x10000
	v_lshlrev_b32_e32 v3, 3, v206
	v_and_b32_e32 v4, 0xc0, v4
	v_lshlrev_b32_e32 v5, 1, v206
	v_and_or_b32 v4, v3, 24, v4
	v_and_b32_e32 v5, 32, v5
	v_and_b32_e32 v3, 0x100, v3
	s_cmp_lg_u32 0, -1
	v_or3_b32 v3, v4, v5, v3
	s_cselect_b32 s4, 0, 0
	v_add_u32_e32 v209, s4, v3
	v_mov_b32_e32 v17, 0
	s_cmp_lt_i32 s27, 3
	v_cmp_gt_u32_e64 s[4:5], 32, v206
	v_lshl_add_u32 v208, v212, 2, s6
	v_lshl_add_u32 v207, v2, 2, s6
	s_waitcnt lgkmcnt(0)
	s_barrier
	s_cbranch_scc1 .LBB0_407
	s_lshl_b32 s6, s39, 8
	s_addk_i32 s6, 0xfc00
	v_lshl_add_u32 v221, v48, 4, s6
	s_add_i32 s6, s1, 0xc0
	v_add_u32_e32 v3, s6, v212
	v_sub_u32_e32 v2, v3, v2
	v_mov_b32_e32 v213, 0
	v_mov_b32_e32 v203, v252
	v_lshl_add_u64 v[196:197], s[54:55], 0, v[0:1]
	v_lshl_add_u64 v[198:199], s[56:57], 0, v[0:1]
	s_mov_b32 s33, 2
	v_subrev_u32_e32 v222, s38, v2
	s_addk_i32 s38, 0xff80
	v_mov_b32_e32 v66, 0
	v_mov_b32_e32 v67, v213
	v_mov_b32_e32 v68, v213
	v_mov_b32_e32 v69, v213
	v_mov_b32_e32 v70, v213
	v_mov_b32_e32 v71, v213
	v_mov_b32_e32 v72, v213
	v_mov_b32_e32 v73, v213
	v_mov_b32_e32 v74, v213
	v_mov_b32_e32 v75, v213
	v_mov_b32_e32 v76, v213
	v_mov_b32_e32 v77, v213
	v_mov_b32_e32 v78, v213
	v_mov_b32_e32 v79, v213
	v_mov_b32_e32 v80, v213
	v_mov_b32_e32 v81, v213
	v_mov_b32_e32 v34, 0
	v_mov_b32_e32 v35, v213
	v_mov_b32_e32 v36, v213
	v_mov_b32_e32 v37, v213
	v_mov_b32_e32 v38, v213
	v_mov_b32_e32 v39, v213
	v_mov_b32_e32 v40, v213
	v_mov_b32_e32 v41, v213
	v_mov_b32_e32 v42, v213
	v_mov_b32_e32 v43, v213
	v_mov_b32_e32 v44, v213
	v_mov_b32_e32 v45, v213
	v_mov_b32_e32 v46, v213
	v_mov_b32_e32 v47, v213
	v_mov_b32_e32 v48, v213
	v_mov_b32_e32 v49, v213
	v_mov_b32_e32 v18, 0
	v_mov_b32_e32 v19, v213
	v_mov_b32_e32 v20, v213
	v_mov_b32_e32 v21, v213
	v_mov_b32_e32 v22, v213
	v_mov_b32_e32 v23, v213
	v_mov_b32_e32 v24, v213
	v_mov_b32_e32 v25, v213
	v_mov_b32_e32 v26, v213
	v_mov_b32_e32 v27, v213
	v_mov_b32_e32 v28, v213
	v_mov_b32_e32 v29, v213
	v_mov_b32_e32 v30, v213
	v_mov_b32_e32 v31, v213
	v_mov_b32_e32 v32, v213
	v_mov_b32_e32 v33, v213
	v_mov_b32_e32 v2, 0
	v_mov_b32_e32 v3, v213
	v_mov_b32_e32 v4, v213
	v_mov_b32_e32 v5, v213
	v_mov_b32_e32 v6, v213
	v_mov_b32_e32 v7, v213
	v_mov_b32_e32 v8, v213
	v_mov_b32_e32 v9, v213
	v_mov_b32_e32 v10, v213
	v_mov_b32_e32 v11, v213
	v_mov_b32_e32 v12, v213
	v_mov_b32_e32 v13, v213
	v_mov_b32_e32 v14, v213
	v_mov_b32_e32 v15, v213
	v_mov_b32_e32 v16, v213
	v_mov_b32_e32 v17, v213
	s_lshl_b32 s32, s38, 8
	s_sub_u32 s32, s32, 0x4000
	s_add_u32 s98, s56, s32
	s_addc_u32 s99, s57, 0
	s_add_u32 s100, s54, s32
	s_addc_u32 s101, s55, 0
	v_readfirstlane_b32 s32, v254
	s_lshr_b32 s32, s32, 6
	s_lshl_b32 s32, s32, 11
	v_and_b32_e32 v218, 3, v254
	v_lshlrev_b32_e32 v218, 4, v218
	v_bfe_u32 v223, v254, 5, 1
	v_lshl_or_b32 v218, v223, 6, v218
	v_bfe_u32 v223, v254, 2, 2
	v_lshl_or_b32 v218, v223, 8, v218
	v_bfe_u32 v223, v254, 6, 1
	v_lshl_or_b32 v218, v223, 10, v218
	v_bfe_u32 v223, v254, 4, 1
	v_lshl_or_b32 v218, v223, 11, v218
	v_bfe_u32 v223, v254, 7, 2
	v_lshl_or_b32 v218, v223, 12, v218
	v_lshrrev_b32_e32 v223, 6, v254
	v_bfe_u32 v224, v254, 4, 2
	v_lshl_or_b32 v223, v223, 3, v224
	v_and_b32_e32 v227, 15, v254
	v_xor_b32_e32 v227, v227, v224
	v_lshlrev_b32_e32 v227, 4, v227
	v_lshl_or_b32 v219, v223, 8, v227
.LBB0_389:
	ds_read_b128 v[98:101], v214 offset:49152
	ds_read_b128 v[102:105], v214 offset:49280
	ds_read_b128 v[106:109], v214 offset:57344
	ds_read_b128 v[110:113], v214 offset:57472
	ds_read_b128 v[178:181], v215 offset:49152
	ds_read_b128 v[184:187], v215 offset:49280
	ds_read_b128 v[188:191], v215 offset:57344
	ds_read_b128 v[226:229], v215 offset:57472
	s_waitcnt lgkmcnt(7)
	v_mfma_f32_32x32x16_bf16 v[50:65], v[98:101], v[158:161], v[50:65]
	ds_read_b128 v[98:101], v216 offset:49152
	ds_read_b128 v[230:233], v216 offset:49280
	ds_read_b128 v[234:237], v216 offset:57344
	ds_read_b128 v[238:241], v216 offset:57472
	ds_read_b128 v[242:245], v217 offset:49152
	ds_read_b128 v[246:249], v217 offset:49280
	ds_read_b128 v[250:253], v217 offset:57344
	ds_read_b128 v[192:195], v217 offset:57472
	v_exp_f32_e32 v128, v128
	v_exp_f32_e32 v129, v129
	v_exp_f32_e32 v126, v126
	v_exp_f32_e32 v127, v127
	v_exp_f32_e32 v124, v124
	v_exp_f32_e32 v125, v125
	s_waitcnt lgkmcnt(11)
	v_mfma_f32_32x32x16_bf16 v[50:65], v[178:181], v[154:157], v[50:65]
	v_exp_f32_e32 v122, v122
	v_exp_f32_e32 v116, v116
	v_exp_f32_e32 v117, v117
	v_exp_f32_e32 v114, v114
	v_exp_f32_e32 v115, v115
	v_cvt_pk_bf16_f32 v178, v175, v177
	v_cvt_pk_bf16_f32 v179, v173, v176
	s_waitcnt lgkmcnt(7)
	v_mfma_f32_32x32x16_bf16 v[50:65], v[98:101], v[150:153], v[50:65]
	v_exp_f32_e32 v101, v118
	v_exp_f32_e32 v118, v119
	v_add_f32_e32 v119, 0, v175
	v_add_f32_e32 v119, v177, v119
	v_add_f32_e32 v119, v173, v119
	v_add_f32_e32 v119, v176, v119
	v_add_f32_e32 v119, v171, v119
	s_waitcnt lgkmcnt(3)
	v_mfma_f32_32x32x16_bf16 v[50:65], v[242:245], v[146:149], v[50:65]
	v_exp_f32_e32 v98, v123
	v_exp_f32_e32 v99, v120
	v_exp_f32_e32 v100, v121
	v_cvt_pk_bf16_f32 v180, v171, v174
	v_cvt_pk_bf16_f32 v181, v170, v172
	s_nop 0
	v_permlane32_swap_b32_e32 v178, v180
	v_mfma_f32_32x32x16_bf16 v[50:65], v[102:105], v[142:145], v[50:65]
	v_add_f32_e32 v102, v174, v119
	v_add_f32_e32 v102, v170, v102
	v_add_f32_e32 v102, v172, v102
	v_add_f32_e32 v102, v164, v102
	v_add_f32_e32 v102, v167, v102
	v_add_f32_e32 v102, v163, v102
	v_add_f32_e32 v102, v165, v102
	v_mfma_f32_32x32x16_bf16 v[50:65], v[184:187], v[138:141], v[50:65]
	v_add_f32_e32 v102, v162, v102
	v_add_f32_e32 v102, v169, v102
	v_add_f32_e32 v102, v166, v102
	v_add_f32_e32 v102, v168, v102
	v_add_f32_e32 v102, v128, v102
	v_add_f32_e32 v102, v129, v102
	v_add_f32_e32 v102, v126, v102
	v_mfma_f32_32x32x16_bf16 v[50:65], v[230:233], v[134:137], v[50:65]
	v_add_f32_e32 v102, v127, v102
	v_add_f32_e32 v102, v124, v102
	v_add_f32_e32 v102, v125, v102
	v_add_f32_e32 v102, v122, v102
	v_add_f32_e32 v102, v98, v102
	v_add_f32_e32 v102, v99, v102
	v_add_f32_e32 v102, v100, v102
	s_waitcnt lgkmcnt(2)
	v_mfma_f32_32x32x16_bf16 v[50:65], v[246:249], v[130:133], v[50:65]
	v_add_f32_e32 v102, v101, v102
	v_add_f32_e32 v102, v118, v102
	v_add_f32_e32 v102, v116, v102
	v_add_f32_e32 v102, v117, v102
	v_add_f32_e32 v102, v114, v102
	v_add_f32_e32 v223, v115, v102
	v_mov_b32_e32 v224, v223
	s_nop 1
	v_permlane32_swap_b32_e32 v223, v224
	v_cvt_pk_bf16_f32 v184, v164, v167
	v_cvt_pk_bf16_f32 v185, v163, v165
	v_cvt_pk_bf16_f32 v186, v162, v169
	v_cvt_pk_bf16_f32 v187, v166, v168
	v_cvt_pk_bf16_f32 v230, v128, v129
	v_cvt_pk_bf16_f32 v231, v126, v127
	v_cvt_pk_bf16_f32 v232, v124, v125
	v_cvt_pk_bf16_f32 v233, v122, v98
	v_cvt_pk_bf16_f32 v242, v99, v100
	v_cvt_pk_bf16_f32 v243, v101, v118
	v_cvt_pk_bf16_f32 v244, v116, v117
	v_cvt_pk_bf16_f32 v245, v114, v115
	v_permlane32_swap_b32_e32 v179, v181
	v_permlane32_swap_b32_e32 v184, v186
	v_permlane32_swap_b32_e32 v185, v187
	v_permlane32_swap_b32_e32 v230, v232
	v_permlane32_swap_b32_e32 v231, v233
	v_permlane32_swap_b32_e32 v242, v244
	v_permlane32_swap_b32_e32 v243, v245
	v_mfma_f32_32x32x16_bf16 v[82:97], v[106:109], v[158:161], v[82:97]
	s_add_i32 s6, s38, 63
	v_mfma_f32_32x32x16_bf16 v[82:97], v[188:191], v[154:157], v[82:97]
	v_mfma_f32_32x32x16_bf16 v[82:97], v[234:237], v[150:153], v[82:97]
	s_waitcnt lgkmcnt(1)
	v_mfma_f32_32x32x16_bf16 v[82:97], v[250:253], v[146:149], v[82:97]
	v_mfma_f32_32x32x16_bf16 v[82:97], v[110:113], v[142:145], v[82:97]
	v_add_u32_e32 v110, 0x100, v221
	global_load_dwordx4 v[114:117], v110, s[52:53]
	global_load_dwordx4 v[118:121], v110, s[52:53] offset:32
	global_load_dwordx4 v[98:101], v110, s[52:53] offset:128
	global_load_dwordx4 v[102:105], v110, s[52:53] offset:160
	global_load_dwordx4 v[122:125], v110, s[52:53] offset:64
	global_load_dwordx4 v[126:129], v110, s[52:53] offset:96
	global_load_dwordx4 v[106:109], v110, s[52:53] offset:192
	s_nop 0
	global_load_dwordx4 v[110:113], v110, s[52:53] offset:224
	v_mfma_f32_32x32x16_bf16 v[82:97], v[226:229], v[138:141], v[82:97]
	v_mfma_f32_32x32x16_bf16 v[82:97], v[238:241], v[134:137], v[82:97]
	s_waitcnt lgkmcnt(0)
	v_mfma_f32_32x32x16_bf16 v[82:97], v[192:195], v[130:133], v[82:97]
	s_add_i32 m0, s32, 0x8000
	v_xor_b32_e32 v162, 64, v219
	global_load_lds_dwordx4 v219, s[98:99]
	s_add_i32 m0, s32, 0x8400
	v_add_u32_e32 v162, 0x400, v162
	global_load_lds_dwordx4 v162, s[98:99]
	s_sub_u32 s98, s98, 0x4000
	s_subb_u32 s99, s99, 0
	ds_read_b64_tr_b16 v[188:189], v209 offset:0
	ds_read_b64_tr_b16 v[190:191], v209 offset:0x800
	ds_read_b64_tr_b16 v[192:193], v209 offset:0x1000
	ds_read_b64_tr_b16 v[194:195], v209 offset:0x1800
	ds_read_b64_tr_b16 v[234:235], v209 offset:0x2000
	ds_read_b64_tr_b16 v[236:237], v209 offset:0x2800
	ds_read_b64_tr_b16 v[238:239], v209 offset:0x3000
	ds_read_b64_tr_b16 v[240:241], v209 offset:0x3800
	s_nop 0
	s_waitcnt lgkmcnt(6)
	v_mfma_f32_32x32x16_bf16 v[66:81], v[178:181], v[188:191], v[66:81]
	ds_read_b64_tr_b16 v[188:189], v209 offset:0x200
	ds_read_b64_tr_b16 v[190:191], v209 offset:0xa00
	s_waitcnt lgkmcnt(6)
	v_mfma_f32_32x32x16_bf16 v[66:81], v[184:187], v[192:195], v[66:81]
	ds_read_b64_tr_b16 v[192:193], v209 offset:0x1200
	ds_read_b64_tr_b16 v[194:195], v209 offset:0x1a00
	s_waitcnt lgkmcnt(6)
	v_mfma_f32_32x32x16_bf16 v[66:81], v[230:233], v[234:237], v[66:81]
	ds_read_b64_tr_b16 v[234:235], v209 offset:0x2200
	ds_read_b64_tr_b16 v[236:237], v209 offset:0x2a00
	ds_read_b64_tr_b16 v[246:247], v209 offset:0x3200
	ds_read_b64_tr_b16 v[248:249], v209 offset:0x3a00
	s_waitcnt lgkmcnt(8)
	v_mfma_f32_32x32x16_bf16 v[66:81], v[242:245], v[238:241], v[66:81]
	s_waitcnt lgkmcnt(6)
	v_mfma_f32_32x32x16_bf16 v[34:49], v[178:181], v[188:191], v[34:49]
	ds_read_b64_tr_b16 v[188:189], v209 offset:0x400
	ds_read_b64_tr_b16 v[190:191], v209 offset:0xc00
	s_waitcnt lgkmcnt(6)
	v_mfma_f32_32x32x16_bf16 v[34:49], v[184:187], v[192:195], v[34:49]
	ds_read_b64_tr_b16 v[192:193], v209 offset:0x1400
	ds_read_b64_tr_b16 v[194:195], v209 offset:0x1c00
	s_waitcnt lgkmcnt(6)
	v_mfma_f32_32x32x16_bf16 v[34:49], v[230:233], v[234:237], v[34:49]
	ds_read_b64_tr_b16 v[234:235], v209 offset:0x2400
	ds_read_b64_tr_b16 v[236:237], v209 offset:0x2c00
	ds_read_b64_tr_b16 v[238:239], v209 offset:0x3400
	ds_read_b64_tr_b16 v[240:241], v209 offset:0x3c00
	s_waitcnt lgkmcnt(8)
	v_mfma_f32_32x32x16_bf16 v[34:49], v[242:245], v[246:249], v[34:49]
	s_waitcnt lgkmcnt(6)
	v_mfma_f32_32x32x16_bf16 v[18:33], v[178:181], v[188:191], v[18:33]
	ds_read_b64_tr_b16 v[188:189], v209 offset:0x600
	ds_read_b64_tr_b16 v[190:191], v209 offset:0xe00
	s_waitcnt lgkmcnt(6)
	v_mfma_f32_32x32x16_bf16 v[18:33], v[184:187], v[192:195], v[18:33]
	ds_read_b64_tr_b16 v[192:193], v209 offset:0x1600
	ds_read_b64_tr_b16 v[194:195], v209 offset:0x1e00
	s_waitcnt lgkmcnt(6)
	v_mfma_f32_32x32x16_bf16 v[18:33], v[230:233], v[234:237], v[18:33]
	ds_read_b64_tr_b16 v[234:235], v209 offset:0x2600
	ds_read_b64_tr_b16 v[236:237], v209 offset:0x2e00
	ds_read_b64_tr_b16 v[246:247], v209 offset:0x3600
	ds_read_b64_tr_b16 v[248:249], v209 offset:0x3e00
	s_waitcnt lgkmcnt(8)
	v_mfma_f32_32x32x16_bf16 v[18:33], v[242:245], v[238:241], v[18:33]
	s_waitcnt lgkmcnt(6)
	v_mfma_f32_32x32x16_bf16 v[2:17], v[178:181], v[188:191], v[2:17]
	s_cmp_le_i32 s6, s1
	s_cselect_b64 s[6:7], -1, 0
	s_cmp_gt_i32 s38, s8
	s_cselect_b64 s[54:55], -1, 0
	s_and_b64 s[6:7], s[6:7], s[54:55]
	s_and_b64 vcc, exec, s[6:7]
	s_waitcnt lgkmcnt(4)
	v_mfma_f32_32x32x16_bf16 v[2:17], v[184:187], v[192:195], v[2:17]
	s_waitcnt lgkmcnt(2)
	v_mfma_f32_32x32x16_bf16 v[2:17], v[230:233], v[234:237], v[2:17]
	s_waitcnt lgkmcnt(0)
	v_mfma_f32_32x32x16_bf16 v[2:17], v[242:245], v[246:249], v[2:17]
	s_cbranch_vccnz .LBB0_391
	v_subrev_u32_e32 v178, 64, v222
	v_cmp_gt_u32_e32 vcc, s11, v178
	v_add_u32_e32 v178, 0xffffefa0, v222
	s_nop 0
	v_cndmask_b32_e32 v50, v202, v50, vcc
	v_cmp_lt_u32_e32 vcc, s68, v178
	v_add_u32_e32 v178, 0xffffefbf, v222
	s_nop 0
	v_cndmask_b32_e32 v82, v202, v82, vcc
	v_cmp_lt_u32_e32 vcc, s68, v178
	v_add_u32_e32 v178, 0xffffef9f, v222
	s_nop 0
	v_cndmask_b32_e32 v51, v202, v51, vcc
	v_cmp_lt_u32_e32 vcc, s68, v178
	v_add_u32_e32 v178, 0xffffefbe, v222
	s_nop 0
	v_cndmask_b32_e32 v83, v202, v83, vcc
	v_cmp_lt_u32_e32 vcc, s68, v178
	v_add_u32_e32 v178, 0xffffef9e, v222
	s_nop 0
	v_cndmask_b32_e32 v52, v202, v52, vcc
	v_cmp_lt_u32_e32 vcc, s68, v178
	v_add_u32_e32 v178, 0xffffefbd, v222
	s_nop 0
	v_cndmask_b32_e32 v84, v202, v84, vcc
	v_cmp_lt_u32_e32 vcc, s68, v178
	v_add_u32_e32 v178, 0xffffef9d, v222
	s_nop 0
	v_cndmask_b32_e32 v53, v202, v53, vcc
	v_cmp_lt_u32_e32 vcc, s68, v178
	v_add_u32_e32 v178, 0xffffefb8, v222
	s_nop 0
	v_cndmask_b32_e32 v85, v202, v85, vcc
	v_cmp_lt_u32_e32 vcc, s68, v178
	v_add_u32_e32 v178, 0xffffef98, v222
	s_nop 0
	v_cndmask_b32_e32 v54, v202, v54, vcc
	v_cmp_lt_u32_e32 vcc, s68, v178
	v_add_u32_e32 v178, 0xffffefb7, v222
	s_nop 0
	v_cndmask_b32_e32 v86, v202, v86, vcc
	v_cmp_lt_u32_e32 vcc, s68, v178
	v_add_u32_e32 v178, 0xffffef97, v222
	s_nop 0
	v_cndmask_b32_e32 v55, v202, v55, vcc
	v_cmp_lt_u32_e32 vcc, s68, v178
	v_add_u32_e32 v178, 0xffffefb6, v222
	s_nop 0
	v_cndmask_b32_e32 v87, v202, v87, vcc
	v_cmp_lt_u32_e32 vcc, s68, v178
	v_add_u32_e32 v178, 0xffffef96, v222
	s_nop 0
	v_cndmask_b32_e32 v56, v202, v56, vcc
	v_cmp_lt_u32_e32 vcc, s68, v178
	v_add_u32_e32 v178, 0xffffefb5, v222
	s_nop 0
	v_cndmask_b32_e32 v88, v202, v88, vcc
	v_cmp_lt_u32_e32 vcc, s68, v178
	v_add_u32_e32 v178, 0xffffef95, v222
	s_nop 0
	v_cndmask_b32_e32 v57, v202, v57, vcc
	v_cmp_lt_u32_e32 vcc, s68, v178
	v_add_u32_e32 v178, 0xffffefb0, v222
	s_nop 0
	v_cndmask_b32_e32 v89, v202, v89, vcc
	v_cmp_lt_u32_e32 vcc, s68, v178
	v_add_u32_e32 v178, 0xffffef90, v222
	s_nop 0
	v_cndmask_b32_e32 v58, v202, v58, vcc
	v_cmp_lt_u32_e32 vcc, s68, v178
	v_add_u32_e32 v178, 0xffffefaf, v222
	s_nop 0
	v_cndmask_b32_e32 v90, v202, v90, vcc
	v_cmp_lt_u32_e32 vcc, s68, v178
	v_add_u32_e32 v178, 0xffffef8f, v222
	s_nop 0
	v_cndmask_b32_e32 v59, v202, v59, vcc
	v_cmp_lt_u32_e32 vcc, s68, v178
	v_add_u32_e32 v178, 0xffffefae, v222
	s_nop 0
	v_cndmask_b32_e32 v91, v202, v91, vcc
	v_cmp_lt_u32_e32 vcc, s68, v178
	v_add_u32_e32 v178, 0xffffef8e, v222
	s_nop 0
	v_cndmask_b32_e32 v60, v202, v60, vcc
	v_cmp_lt_u32_e32 vcc, s68, v178
	v_add_u32_e32 v178, 0xffffefad, v222
	s_nop 0
	v_cndmask_b32_e32 v92, v202, v92, vcc
	v_cmp_lt_u32_e32 vcc, s68, v178
	v_add_u32_e32 v178, 0xffffef8d, v222
	s_nop 0
	v_cndmask_b32_e32 v61, v202, v61, vcc
	v_cmp_lt_u32_e32 vcc, s68, v178
	v_add_u32_e32 v178, 0xffffefa8, v222
	s_nop 0
	v_cndmask_b32_e32 v93, v202, v93, vcc
	v_cmp_lt_u32_e32 vcc, s68, v178
	v_add_u32_e32 v178, 0xffffef88, v222
	s_nop 0
	v_cndmask_b32_e32 v62, v202, v62, vcc
	v_cmp_lt_u32_e32 vcc, s68, v178
	v_add_u32_e32 v178, 0xffffefa7, v222
	s_nop 0
	v_cndmask_b32_e32 v94, v202, v94, vcc
	v_cmp_lt_u32_e32 vcc, s68, v178
	v_add_u32_e32 v178, 0xffffef87, v222
	s_nop 0
	v_cndmask_b32_e32 v63, v202, v63, vcc
	v_cmp_lt_u32_e32 vcc, s68, v178
	v_add_u32_e32 v178, 0xffffefa6, v222
	s_nop 0
	v_cndmask_b32_e32 v95, v202, v95, vcc
	v_cmp_lt_u32_e32 vcc, s68, v178
	v_add_u32_e32 v178, 0xffffef86, v222
	s_nop 0
	v_cndmask_b32_e32 v64, v202, v64, vcc
	v_cmp_lt_u32_e32 vcc, s68, v178
	v_add_u32_e32 v178, 0xffffefa5, v222
	s_nop 0
	v_cndmask_b32_e32 v96, v202, v96, vcc
	v_cmp_lt_u32_e32 vcc, s68, v178
	v_add_u32_e32 v178, 0xffffef85, v222
	s_nop 0
	v_cndmask_b32_e32 v65, v202, v65, vcc
	v_cmp_lt_u32_e32 vcc, s68, v178
	s_nop 1
	v_cndmask_b32_e32 v97, v202, v97, vcc
.LBB0_391:
	v_max_f32_e32 v178, v51, v51
	v_max_f32_e32 v179, v50, v50
	v_max_f32_e32 v178, v179, v178
	v_max3_f32 v178, v178, v52, v53
	v_max3_f32 v178, v178, v54, v55
	v_max3_f32 v178, v178, v56, v57
	v_max3_f32 v178, v178, v58, v59
	v_max3_f32 v178, v178, v60, v61
	v_max3_f32 v178, v178, v62, v63
	v_max3_f32 v178, v178, v64, v65
	v_max3_f32 v178, v178, v82, v83
	v_max3_f32 v178, v178, v84, v85
	v_max3_f32 v178, v178, v86, v87
	v_max3_f32 v178, v178, v88, v89
	v_max3_f32 v178, v178, v90, v91
	v_max3_f32 v178, v178, v92, v93
	v_max3_f32 v178, v178, v94, v95
	v_max3_f32 v178, v178, v96, v97
	v_mov_b32_e32 v179, v178
	s_nop 1
	v_permlane32_swap_b32_e32 v178, v179
	v_max_f32_e32 v179, v179, v179
	v_max_f32_e32 v178, v178, v178
	v_max_f32_e32 v178, v178, v179
	v_max_f32_e32 v180, v182, v182
	v_sub_f32_e32 v179, v178, v182
	v_max_f32_e32 v178, v180, v178
	v_sub_f32_e32 v180, v182, v178
	v_mul_f32_e32 v180, 0x3e0293ee, v180
	v_mul_f32_e32 v179, 0x3db504f3, v179
	v_exp_f32_e32 v180, v180
	v_cmp_ge_f32_e32 vcc, s69, v179
	s_cmp_eq_u64 vcc, exec
	s_cselect_b64 s[6:7], -1, 0
	s_barrier
	v_cndmask_b32_e64 v225, v180, 1.0, s[6:7]
	v_cmp_gt_f32_e32 vcc, 1.0, v225
	s_add_i32 m0, s32, 0x0
	v_add_u32_e32 v162, 0x80, v218
	global_load_lds_dwordx4 v218, s[100:101]
	s_add_i32 m0, s32, 0x400
	s_nop 0
	global_load_lds_dwordx4 v162, s[100:101]
	s_sub_u32 s100, s100, 0x4000
	s_subb_u32 s101, s101, 0
	s_cbranch_vccz .LBB0_395
	s_and_saveexec_b64 s[54:55], s[4:5]
	ds_write_b32 v208, v225 offset:128
	s_or_b64 exec, exec, s[54:55]
	s_waitcnt lgkmcnt(0)
	ds_read_b128 v[184:187], v207 offset:224
	ds_read_b128 v[188:191], v207 offset:192
	ds_read_b128 v[192:195], v207 offset:160
	ds_read_b128 v[230:233], v207 offset:128
	s_waitcnt lgkmcnt(3)
	v_pk_mul_f32 v[80:81], v[80:81], v[186:187]
	s_waitcnt lgkmcnt(2)
	v_pk_mul_f32 v[76:77], v[76:77], v[190:191]
	s_waitcnt lgkmcnt(1)
	v_pk_mul_f32 v[72:73], v[72:73], v[194:195]
	s_waitcnt lgkmcnt(0)
	v_pk_mul_f32 v[68:69], v[68:69], v[232:233]
	v_pk_mul_f32 v[78:79], v[78:79], v[184:185]
	v_pk_mul_f32 v[74:75], v[74:75], v[188:189]
	v_pk_mul_f32 v[70:71], v[70:71], v[192:193]
	v_pk_mul_f32 v[66:67], v[66:67], v[230:231]
	v_pk_mul_f32 v[48:49], v[48:49], v[186:187]
	v_pk_mul_f32 v[44:45], v[44:45], v[190:191]
	v_pk_mul_f32 v[40:41], v[40:41], v[194:195]
	v_pk_mul_f32 v[36:37], v[36:37], v[232:233]
	v_pk_mul_f32 v[46:47], v[46:47], v[184:185]
	v_pk_mul_f32 v[42:43], v[42:43], v[188:189]
	v_pk_mul_f32 v[38:39], v[38:39], v[192:193]
	v_pk_mul_f32 v[34:35], v[34:35], v[230:231]
	v_pk_mul_f32 v[32:33], v[32:33], v[186:187]
	v_pk_mul_f32 v[28:29], v[28:29], v[190:191]
	v_pk_mul_f32 v[24:25], v[24:25], v[194:195]
	v_pk_mul_f32 v[20:21], v[20:21], v[232:233]
	v_pk_mul_f32 v[30:31], v[30:31], v[184:185]
	v_pk_mul_f32 v[26:27], v[26:27], v[188:189]
	v_pk_mul_f32 v[22:23], v[22:23], v[192:193]
	v_pk_mul_f32 v[18:19], v[18:19], v[230:231]
	v_pk_mul_f32 v[16:17], v[16:17], v[186:187]
	v_pk_mul_f32 v[12:13], v[12:13], v[190:191]
	v_pk_mul_f32 v[8:9], v[8:9], v[194:195]
	v_pk_mul_f32 v[4:5], v[4:5], v[232:233]
	v_pk_mul_f32 v[14:15], v[14:15], v[184:185]
	v_pk_mul_f32 v[10:11], v[10:11], v[188:189]
	v_pk_mul_f32 v[6:7], v[6:7], v[192:193]
	v_pk_mul_f32 v[2:3], v[2:3], v[230:231]
.LBB0_395:
	v_cndmask_b32_e64 v226, v178, v182, s[6:7]
	v_mul_f32_e32 v178, 0xbe0293ee, v226
	v_fmamk_f32 v50, v50, 0x3e0293ee, v178
	v_fmamk_f32 v51, v51, 0x3e0293ee, v178
	v_fmamk_f32 v52, v52, 0x3e0293ee, v178
	v_fmamk_f32 v53, v53, 0x3e0293ee, v178
	v_fmamk_f32 v54, v54, 0x3e0293ee, v178
	v_fmamk_f32 v55, v55, 0x3e0293ee, v178
	v_fmamk_f32 v56, v56, 0x3e0293ee, v178
	v_fmamk_f32 v57, v57, 0x3e0293ee, v178
	v_fmamk_f32 v58, v58, 0x3e0293ee, v178
	v_fmamk_f32 v59, v59, 0x3e0293ee, v178
	v_fmamk_f32 v60, v60, 0x3e0293ee, v178
	v_fmamk_f32 v61, v61, 0x3e0293ee, v178
	v_fmamk_f32 v62, v62, 0x3e0293ee, v178
	v_fmamk_f32 v63, v63, 0x3e0293ee, v178
	v_fmamk_f32 v64, v64, 0x3e0293ee, v178
	v_fmamk_f32 v65, v65, 0x3e0293ee, v178
	v_exp_f32_e32 v50, v50
	v_exp_f32_e32 v51, v51
	v_exp_f32_e32 v52, v52
	v_exp_f32_e32 v53, v53
	v_exp_f32_e32 v54, v54
	v_exp_f32_e32 v55, v55
	v_exp_f32_e32 v56, v56
	v_exp_f32_e32 v57, v57
	v_exp_f32_e32 v58, v58
	v_exp_f32_e32 v59, v59
	v_exp_f32_e32 v60, v60
	v_exp_f32_e32 v61, v61
	v_exp_f32_e32 v62, v62
	v_exp_f32_e32 v63, v63
	v_exp_f32_e32 v64, v64
	v_exp_f32_e32 v65, v65
	v_fmamk_f32 v82, v82, 0x3e0293ee, v178
	v_fmamk_f32 v83, v83, 0x3e0293ee, v178
	v_fmamk_f32 v84, v84, 0x3e0293ee, v178
	v_fmamk_f32 v85, v85, 0x3e0293ee, v178
	v_fmamk_f32 v86, v86, 0x3e0293ee, v178
	v_fmamk_f32 v87, v87, 0x3e0293ee, v178
	v_fmamk_f32 v88, v88, 0x3e0293ee, v178
	v_fmamk_f32 v89, v89, 0x3e0293ee, v178
	v_fmamk_f32 v90, v90, 0x3e0293ee, v178
	v_fmamk_f32 v91, v91, 0x3e0293ee, v178
	v_fmamk_f32 v92, v92, 0x3e0293ee, v178
	v_fmamk_f32 v93, v93, 0x3e0293ee, v178
	v_fmamk_f32 v94, v94, 0x3e0293ee, v178
	v_fmamk_f32 v95, v95, 0x3e0293ee, v178
	v_fmamk_f32 v96, v96, 0x3e0293ee, v178
	v_fmac_f32_e32 v178, 0x3e0293ee, v97
	s_waitcnt lgkmcnt(0)
	s_waitcnt vmcnt(2)
	s_barrier
	ds_read_b128 v[230:233], v214 offset:32768
	ds_read_b128 v[234:237], v214 offset:40960
	ds_read_b128 v[238:241], v215 offset:32768
	ds_read_b128 v[242:245], v215 offset:40960
	ds_read_b128 v[180:183], v216 offset:32768
	ds_read_b128 v[184:187], v216 offset:40960
	ds_read_b128 v[246:249], v217 offset:32768
	ds_read_b128 v[250:253], v217 offset:40960
	v_exp_f32_e32 v97, v178
	v_add_f32_e32 v178, 0, v50
	v_add_f32_e32 v178, v51, v178
	s_waitcnt lgkmcnt(7)
	v_mfma_f32_32x32x16_bf16 v[114:129], v[230:233], v[158:161], v[114:129]
	v_add_f32_e32 v178, v52, v178
	v_add_f32_e32 v178, v53, v178
	v_add_f32_e32 v178, v54, v178
	v_add_f32_e32 v178, v55, v178
	v_add_f32_e32 v178, v56, v178
	v_add_f32_e32 v178, v57, v178
	v_add_f32_e32 v178, v58, v178
	s_waitcnt lgkmcnt(6)
	v_mfma_f32_32x32x16_bf16 v[98:113], v[234:237], v[158:161], v[98:113]
	ds_read_b128 v[230:233], v214 offset:32896
	ds_read_b128 v[234:237], v214 offset:41088
	v_add_f32_e32 v178, v59, v178
	v_add_f32_e32 v178, v60, v178
	v_add_f32_e32 v178, v61, v178
	v_exp_f32_e32 v82, v82
	v_add_f32_e32 v178, v62, v178
	v_exp_f32_e32 v83, v83
	s_waitcnt lgkmcnt(7)
	v_mfma_f32_32x32x16_bf16 v[114:129], v[238:241], v[154:157], v[114:129]
	v_add_f32_e32 v178, v63, v178
	v_exp_f32_e32 v84, v84
	v_add_f32_e32 v178, v64, v178
	v_exp_f32_e32 v85, v85
	v_add_f32_e32 v178, v65, v178
	v_exp_f32_e32 v86, v86
	v_add_f32_e32 v178, v82, v178
	s_waitcnt lgkmcnt(6)
	v_mfma_f32_32x32x16_bf16 v[98:113], v[242:245], v[154:157], v[98:113]
	ds_read_b128 v[238:241], v215 offset:32896
	ds_read_b128 v[242:245], v215 offset:41088
	v_exp_f32_e32 v87, v87
	v_add_f32_e32 v178, v83, v178
	v_exp_f32_e32 v88, v88
	v_add_f32_e32 v178, v84, v178
	v_exp_f32_e32 v89, v89
	v_add_f32_e32 v178, v85, v178
	s_waitcnt lgkmcnt(7)
	v_mfma_f32_32x32x16_bf16 v[114:129], v[180:183], v[150:153], v[114:129]
	v_exp_f32_e32 v90, v90
	v_add_f32_e32 v178, v86, v178
	v_exp_f32_e32 v91, v91
	v_add_f32_e32 v178, v87, v178
	v_exp_f32_e32 v92, v92
	v_add_f32_e32 v178, v88, v178
	v_exp_f32_e32 v93, v93
	s_waitcnt lgkmcnt(6)
	v_mfma_f32_32x32x16_bf16 v[98:113], v[184:187], v[150:153], v[98:113]
	ds_read_b128 v[180:183], v216 offset:32896
	ds_read_b128 v[184:187], v216 offset:41088
	v_add_f32_e32 v178, v89, v178
	v_exp_f32_e32 v94, v94
	v_add_f32_e32 v178, v90, v178
	v_exp_f32_e32 v95, v95
	v_add_f32_e32 v178, v91, v178
	v_exp_f32_e32 v96, v96
	s_waitcnt lgkmcnt(7)
	v_mfma_f32_32x32x16_bf16 v[114:129], v[246:249], v[146:149], v[114:129]
	v_add_f32_e32 v178, v92, v178
	v_add_f32_e32 v178, v93, v178
	v_add_f32_e32 v178, v94, v178
	v_add_f32_e32 v178, v95, v178
	v_add_f32_e32 v178, v96, v178
	v_add_f32_e32 v227, v97, v178
	v_mov_b32_e32 v228, v227
	s_waitcnt lgkmcnt(6)
	v_mfma_f32_32x32x16_bf16 v[98:113], v[250:253], v[146:149], v[98:113]
	ds_read_b128 v[246:249], v217 offset:32896
	ds_read_b128 v[250:253], v217 offset:41088
	v_permlane32_swap_b32_e32 v227, v228
	s_waitcnt lgkmcnt(7)
	v_mfma_f32_32x32x16_bf16 v[114:129], v[230:233], v[142:145], v[114:129]
	s_waitcnt lgkmcnt(6)
	v_mfma_f32_32x32x16_bf16 v[98:113], v[234:237], v[142:145], v[98:113]
	s_waitcnt lgkmcnt(5)
	v_mfma_f32_32x32x16_bf16 v[114:129], v[238:241], v[138:141], v[114:129]
	s_waitcnt lgkmcnt(4)
	v_mfma_f32_32x32x16_bf16 v[98:113], v[242:245], v[138:141], v[98:113]
	s_waitcnt lgkmcnt(3)
	v_mfma_f32_32x32x16_bf16 v[114:129], v[180:183], v[134:137], v[114:129]
	s_waitcnt lgkmcnt(2)
	v_mfma_f32_32x32x16_bf16 v[98:113], v[184:187], v[134:137], v[98:113]
	v_cvt_pk_bf16_f32 v178, v50, v51
	v_cvt_pk_bf16_f32 v179, v52, v53
	s_waitcnt lgkmcnt(1)
	v_mfma_f32_32x32x16_bf16 v[114:129], v[246:249], v[130:133], v[114:129]
	v_cvt_pk_bf16_f32 v180, v54, v55
	v_cvt_pk_bf16_f32 v181, v56, v57
	v_cvt_pk_bf16_f32 v182, v58, v59
	v_cvt_pk_bf16_f32 v183, v60, v61
	s_nop 0
	v_permlane32_swap_b32_e32 v178, v180
	s_waitcnt lgkmcnt(0)
	v_mfma_f32_32x32x16_bf16 v[98:113], v[250:253], v[130:133], v[98:113]
	v_cvt_pk_bf16_f32 v184, v62, v63
	v_cvt_pk_bf16_f32 v185, v64, v65
	v_cvt_pk_bf16_f32 v186, v82, v83
	v_cvt_pk_bf16_f32 v187, v84, v85
	v_cvt_pk_bf16_f32 v188, v86, v87
	v_cvt_pk_bf16_f32 v189, v88, v89
	v_cvt_pk_bf16_f32 v190, v90, v91
	v_cvt_pk_bf16_f32 v191, v92, v93
	v_cvt_pk_bf16_f32 v192, v94, v95
	v_cvt_pk_bf16_f32 v193, v96, v97
	v_permlane32_swap_b32_e32 v179, v181
	v_permlane32_swap_b32_e32 v182, v184
	v_permlane32_swap_b32_e32 v183, v185
	v_permlane32_swap_b32_e32 v186, v188
	v_permlane32_swap_b32_e32 v187, v189
	v_permlane32_swap_b32_e32 v190, v192
	v_permlane32_swap_b32_e32 v191, v193
	s_add_i32 s6, s33, 1
	s_cmp_lt_i32 s6, s27
	s_cselect_b64 s[54:55], -1, 0
	s_cmp_ge_i32 s6, s27
	s_cbranch_scc1 .LBB0_397
	global_load_dwordx4 v[50:53], v221, s[52:53]
	global_load_dwordx4 v[54:57], v221, s[52:53] offset:32
	global_load_dwordx4 v[82:85], v221, s[52:53] offset:128
	global_load_dwordx4 v[86:89], v221, s[52:53] offset:160
	global_load_dwordx4 v[58:61], v221, s[52:53] offset:64
	global_load_dwordx4 v[62:65], v221, s[52:53] offset:96
	global_load_dwordx4 v[90:93], v221, s[52:53] offset:192
	global_load_dwordx4 v[94:97], v221, s[52:53] offset:224
	s_add_i32 m0, s32, 0xc000
	v_xor_b32_e32 v162, 64, v219
	global_load_lds_dwordx4 v219, s[98:99]
	s_add_i32 m0, s32, 0xc400
	v_add_u32_e32 v162, 0x400, v162
	global_load_lds_dwordx4 v162, s[98:99]
	s_sub_u32 s98, s98, 0x4000
	s_subb_u32 s99, s99, 0

.LBB0_399:
	v_max_f32_e32 v178, v115, v115
	v_max_f32_e32 v179, v114, v114
	v_max_f32_e32 v178, v179, v178
	v_max3_f32 v178, v178, v116, v117
	v_max3_f32 v178, v178, v118, v119
	v_max3_f32 v178, v178, v120, v121
	v_max3_f32 v178, v178, v122, v123
	v_max3_f32 v178, v178, v124, v125
	v_max3_f32 v178, v178, v126, v127
	v_max3_f32 v178, v178, v128, v129
	v_max3_f32 v178, v178, v98, v99
	v_max3_f32 v178, v178, v100, v101
	v_max3_f32 v178, v178, v102, v103
	v_max3_f32 v178, v178, v104, v105
	v_max3_f32 v178, v178, v106, v107
	v_max3_f32 v178, v178, v108, v109
	v_max3_f32 v178, v178, v110, v111
	v_max3_f32 v178, v178, v112, v113
	v_mov_b32_e32 v179, v178
	s_nop 1
	v_permlane32_swap_b32_e32 v178, v179
	v_max_f32_e32 v179, v179, v179
	v_max_f32_e32 v178, v178, v178
	v_max_f32_e32 v178, v178, v179
	v_sub_f32_e32 v179, v178, v226
	v_mul_f32_e32 v179, 0x3db504f3, v179
	v_cmp_ge_f32_e32 vcc, s69, v179
	s_cmp_eq_u64 vcc, exec
	s_cselect_b64 s[6:7], -1, 0
	s_andn2_b64 vcc, exec, s[54:55]
	s_barrier
	s_cbranch_vccz .Lat_ev_load
	s_waitcnt vmcnt(0)
	s_branch .LBB0_401
.Lat_ev_load:
	s_add_i32 m0, s32, 0x4000
	v_add_u32_e32 v162, 0x80, v218
	global_load_lds_dwordx4 v218, s[100:101]
	s_add_i32 m0, s32, 0x4400
	s_nop 0
	global_load_lds_dwordx4 v162, s[100:101]
	s_sub_u32 s100, s100, 0x4000
	s_subb_u32 s101, s101, 0
.LBB0_401:
	v_max_f32_e32 v162, v226, v226
	v_max_f32_e32 v162, v162, v178
	v_sub_f32_e32 v163, v226, v162
	v_mul_f32_e32 v163, 0x3e0293ee, v163
	v_exp_f32_e32 v163, v163
	s_nop 0
	v_cndmask_b32_e64 v178, v163, 1.0, s[6:7]
	v_cmp_gt_f32_e32 vcc, 1.0, v178
	s_cbranch_vccz .LBB0_405
	s_and_saveexec_b64 s[54:55], s[4:5]
	ds_write_b32 v208, v178 offset:128
	s_or_b64 exec, exec, s[54:55]
	s_waitcnt lgkmcnt(0)
	ds_read_b128 v[164:167], v207 offset:224
	ds_read_b128 v[168:171], v207 offset:192
	ds_read_b128 v[172:175], v207 offset:160
	ds_read_b128 v[180:183], v207 offset:128
	s_waitcnt lgkmcnt(3)
	v_pk_mul_f32 v[80:81], v[80:81], v[166:167]
	s_waitcnt lgkmcnt(2)
	v_pk_mul_f32 v[76:77], v[76:77], v[170:171]
	s_waitcnt lgkmcnt(1)
	v_pk_mul_f32 v[72:73], v[72:73], v[174:175]
	s_waitcnt lgkmcnt(0)
	v_pk_mul_f32 v[68:69], v[68:69], v[182:183]
	v_pk_mul_f32 v[78:79], v[78:79], v[164:165]
	v_pk_mul_f32 v[74:75], v[74:75], v[168:169]
	v_pk_mul_f32 v[70:71], v[70:71], v[172:173]
	v_pk_mul_f32 v[66:67], v[66:67], v[180:181]
	v_pk_mul_f32 v[48:49], v[48:49], v[166:167]
	v_pk_mul_f32 v[44:45], v[44:45], v[170:171]
	v_pk_mul_f32 v[40:41], v[40:41], v[174:175]
	v_pk_mul_f32 v[36:37], v[36:37], v[182:183]
	v_pk_mul_f32 v[46:47], v[46:47], v[164:165]
	v_pk_mul_f32 v[42:43], v[42:43], v[168:169]
	v_pk_mul_f32 v[38:39], v[38:39], v[172:173]
	v_pk_mul_f32 v[34:35], v[34:35], v[180:181]
	v_pk_mul_f32 v[32:33], v[32:33], v[166:167]
	v_pk_mul_f32 v[28:29], v[28:29], v[170:171]
	v_pk_mul_f32 v[24:25], v[24:25], v[174:175]
	v_pk_mul_f32 v[20:21], v[20:21], v[182:183]
	v_pk_mul_f32 v[30:31], v[30:31], v[164:165]
	v_pk_mul_f32 v[26:27], v[26:27], v[168:169]
	v_pk_mul_f32 v[22:23], v[22:23], v[172:173]
	v_pk_mul_f32 v[18:19], v[18:19], v[180:181]
	v_pk_mul_f32 v[16:17], v[16:17], v[166:167]
	v_pk_mul_f32 v[12:13], v[12:13], v[170:171]
	v_pk_mul_f32 v[8:9], v[8:9], v[174:175]
	v_pk_mul_f32 v[4:5], v[4:5], v[182:183]
	v_pk_mul_f32 v[14:15], v[14:15], v[164:165]
	v_pk_mul_f32 v[10:11], v[10:11], v[168:169]
	v_pk_mul_f32 v[6:7], v[6:7], v[172:173]
	v_pk_mul_f32 v[2:3], v[2:3], v[180:181]
.LBB0_405:
	v_cndmask_b32_e64 v182, v162, v226, s[6:7]
	v_mul_f32_e32 v180, 0xbe0293ee, v182
	v_mov_b32_e32 v183, v180
	v_fmamk_f32 v162, v114, 0x3e0293ee, v180
	v_fmamk_f32 v163, v115, 0x3e0293ee, v180
	v_fmamk_f32 v164, v116, 0x3e0293ee, v180
	v_fmamk_f32 v165, v117, 0x3e0293ee, v180
	v_fmamk_f32 v166, v118, 0x3e0293ee, v180
	v_fmamk_f32 v167, v119, 0x3e0293ee, v180
	v_fmamk_f32 v168, v120, 0x3e0293ee, v180
	v_fmamk_f32 v169, v121, 0x3e0293ee, v180
	v_fmamk_f32 v179, v122, 0x3e0293ee, v180
	v_fmamk_f32 v181, v123, 0x3e0293ee, v180
	v_fmamk_f32 v124, v124, 0x3e0293ee, v180
	v_fmamk_f32 v125, v125, 0x3e0293ee, v180
	v_fmamk_f32 v126, v126, 0x3e0293ee, v180
	v_fmamk_f32 v127, v127, 0x3e0293ee, v180
	v_fmamk_f32 v128, v128, 0x3e0293ee, v180
	v_fmac_f32_e32 v183, 0x3e0293ee, v129
	v_exp_f32_e32 v175, v162
	v_exp_f32_e32 v177, v163
	v_exp_f32_e32 v173, v164
	v_exp_f32_e32 v176, v165
	v_exp_f32_e32 v171, v166
	v_exp_f32_e32 v174, v167
	v_exp_f32_e32 v170, v168
	v_exp_f32_e32 v172, v169
	v_exp_f32_e32 v164, v179
	v_exp_f32_e32 v167, v181
	v_exp_f32_e32 v163, v124
	v_exp_f32_e32 v165, v125
	v_exp_f32_e32 v162, v126
	v_exp_f32_e32 v169, v127
	v_exp_f32_e32 v166, v128
	v_exp_f32_e32 v168, v183
	v_pk_fma_f32 v[128:129], v[98:99], s[16:17], v[180:181] op_sel_hi:[1,0,0]
	v_add_f32_e32 v98, v223, v224
	v_fmac_f32_e32 v98, v220, v213
	v_add_f32_e32 v213, v227, v228
	s_addk_i32 s38, 0xff80
	s_add_i32 s33, s33, 2
	v_pk_fma_f32 v[114:115], v[112:113], s[16:17], v[180:181] op_sel_hi:[1,0,0]
	v_pk_fma_f32 v[116:117], v[110:111], s[16:17], v[180:181] op_sel_hi:[1,0,0]
	v_pk_fma_f32 v[118:119], v[108:109], s[16:17], v[180:181] op_sel_hi:[1,0,0]
	v_pk_fma_f32 v[120:121], v[106:107], s[16:17], v[180:181] op_sel_hi:[1,0,0]
	v_pk_fma_f32 v[122:123], v[104:105], s[16:17], v[180:181] op_sel_hi:[1,0,0]
	v_pk_fma_f32 v[124:125], v[102:103], s[16:17], v[180:181] op_sel_hi:[1,0,0]
	v_pk_fma_f32 v[126:127], v[100:101], s[16:17], v[180:181] op_sel_hi:[1,0,0]
	v_fmac_f32_e32 v213, v98, v225
	v_add_u32_e32 v221, 0xfffffe00, v221
	s_cmp_ge_i32 s33, s27
	v_add_u32_e32 v222, 0x80, v222
	s_waitcnt lgkmcnt(0)
	s_waitcnt vmcnt(2)
	s_barrier
	s_cbranch_scc1 .LBB0_408
	v_mov_b32_e32 v220, v178
	s_branch .LBB0_389

	.amdhsa_kernel _Z8fwd_mega6Params
		.amdhsa_group_segment_fixed_size 0
		.amdhsa_private_segment_fixed_size 0
		.amdhsa_kernarg_size 440
		.amdhsa_user_sgpr_count 2
		.amdhsa_user_sgpr_dispatch_ptr 0
		.amdhsa_user_sgpr_queue_ptr 0
		.amdhsa_user_sgpr_kernarg_segment_ptr 1
		.amdhsa_user_sgpr_dispatch_id 0
		.amdhsa_user_sgpr_kernarg_preload_length 0
		.amdhsa_user_sgpr_kernarg_preload_offset 0
		.amdhsa_user_sgpr_private_segment_size 0
		.amdhsa_uses_dynamic_stack 0
		.amdhsa_enable_private_segment 0
		.amdhsa_system_sgpr_workgroup_id_x 1
		.amdhsa_system_sgpr_workgroup_id_y 0
		.amdhsa_system_sgpr_workgroup_id_z 0
		.amdhsa_system_sgpr_workgroup_info 0
		.amdhsa_system_vgpr_workitem_id 2
		.amdhsa_next_free_vgpr 256
		.amdhsa_next_free_sgpr 102
		.amdhsa_accum_offset 256
		.amdhsa_reserve_vcc 1
		.amdhsa_float_round_mode_32 0
		.amdhsa_float_round_mode_16_64 0
		.amdhsa_float_denorm_mode_32 3
		.amdhsa_float_denorm_mode_16_64 3
		.amdhsa_dx10_clamp 1
		.amdhsa_ieee_mode 1
		.amdhsa_fp16_overflow 0
		.amdhsa_tg_split 0
		.amdhsa_exception_fp_ieee_invalid_op 0
		.amdhsa_exception_fp_denorm_src 0
		.amdhsa_exception_fp_ieee_div_zero 0
		.amdhsa_exception_fp_ieee_overflow 0
		.amdhsa_exception_fp_ieee_underflow 0
		.amdhsa_exception_fp_ieee_inexact 0
		.amdhsa_exception_int_div_zero 0
	.end_amdhsa_kernel

amdhsa.kernels:
  - .agpr_count:     0
    .args:
      - .offset:         0
        .size:           184
        .value_kind:     by_value
      - .offset:         184
        .size:           4
        .value_kind:     hidden_block_count_x
      - .offset:         188
        .size:           4
        .value_kind:     hidden_block_count_y
      - .offset:         192
        .size:           4
        .value_kind:     hidden_block_count_z
      - .offset:         196
        .size:           2
        .value_kind:     hidden_group_size_x
      - .offset:         198
        .size:           2
        .value_kind:     hidden_group_size_y
      - .offset:         200
        .size:           2
        .value_kind:     hidden_group_size_z
      - .offset:         202
        .size:           2
        .value_kind:     hidden_remainder_x
      - .offset:         204
        .size:           2
        .value_kind:     hidden_remainder_y
      - .offset:         206
        .size:           2
        .value_kind:     hidden_remainder_z
      - .offset:         224
        .size:           8
        .value_kind:     hidden_global_offset_x
      - .offset:         232
        .size:           8
        .value_kind:     hidden_global_offset_y
      - .offset:         240
        .size:           8
        .value_kind:     hidden_global_offset_z
      - .offset:         248
        .size:           2
        .value_kind:     hidden_grid_dims
      - .offset:         272
        .size:           8
        .value_kind:     hidden_multigrid_sync_arg
      - .offset:         304
        .size:           4
        .value_kind:     hidden_dynamic_lds_size
    .group_segment_fixed_size: 0
    .kernarg_segment_align: 8
    .kernarg_segment_size: 440
    .language:       OpenCL C
    .language_version:
      - 2
      - 0
    .max_flat_workgroup_size: 512
    .name:           _Z8fwd_mega6Params
    .private_segment_fixed_size: 0
    .sgpr_count:     108
    .sgpr_spill_count: 12
    .symbol:         _Z8fwd_mega6Params.kd
    .uniform_work_group_size: 1
    .uses_dynamic_stack: false
    .vgpr_count:     256
    .vgpr_spill_count: 0
    .wavefront_size: 64
